# stack: SEL list reads fused, top-k compares paired, PB prologue loop double-batched, on top of post_norm pipelining and earlier epilogue/flag/prio edits
# baseline (speedup 1.0000x reference)
; DI void prologue(const P& p, ldsp lds, int G, int wv) {
;     ...
;     for (int it = gw; it < 2 * 2 * 2 * 16; it += NGW) {
;         const int kc = it & 15, eh = (it >> 4) & 1, kv = (it >> 5) & 1, l = it >> 6;
;         const float* pos = (kv ? p.cpv : p.cpk) + (size_t)l * 4096; const float* w = (kv ? p.cwv : p.cwk) + (size_t)l * 4096 * 128;
;         const int e = eh * 64 + lane; float a = 0.f;
;         for (int k = kc * 256; k < kc * 256 + 256; ++k) a += pos[k] * w[(size_t)k * 128 + e];
;         atomicAdd(PB + (l * 2 + kv) * 128 + e, a);
.LBB0_97:
	v_lshl_add_u64 v[38:39], v[10:11], 0, s[10:11]
	global_load_dword v6, v[12:13], off offset:-3584
	global_load_dwordx4 v[22:25], v[38:39], off offset:48
	global_load_dwordx4 v[26:29], v[38:39], off offset:16
	global_load_dwordx4 v[30:33], v[38:39], off
	v_add_co_u32_e32 v40, vcc, s21, v12
	s_add_u32 s10, s10, 64
	s_nop 0
	v_addc_co_u32_e32 v41, vcc, -1, v13, vcc
	global_load_dword v42, v[40:41], off offset:-3584
	global_load_dword v43, v[40:41], off offset:-3072
	global_load_dword v44, v[40:41], off offset:-2560
	global_load_dword v45, v[40:41], off offset:-2048
	global_load_dword v46, v[40:41], off offset:-1536
	global_load_dword v47, v[40:41], off offset:-1024
	global_load_dword v48, v[40:41], off offset:-512
	global_load_dword v49, v[12:13], off offset:-4096
	global_load_dwordx4 v[34:37], v[38:39], off offset:32
	global_load_dword v50, v[12:13], off offset:-3072
	global_load_dword v51, v[12:13], off offset:-2560
	global_load_dword v52, v[12:13], off offset:-2048
	global_load_dword v53, v[12:13], off offset:-1536
	global_load_dword v54, v[12:13], off offset:-1024
	global_load_dword v55, v[12:13], off offset:-512
	global_load_dword v38, v[12:13], off
	s_addc_u32 s11, s11, 0
	v_lshl_add_u64 v[12:13], v[12:13], 0, s[8:9]
	v_lshl_add_u64 v[78:79], v[10:11], 0, s[10:11]
	global_load_dword v96, v[12:13], off offset:-3584
	global_load_dwordx4 v[62:65], v[78:79], off offset:48
	global_load_dwordx4 v[66:69], v[78:79], off offset:16
	global_load_dwordx4 v[70:73], v[78:79], off
	v_add_co_u32_e32 v80, vcc, s21, v12
	s_add_u32 s10, s10, 64
	s_nop 0
	v_addc_co_u32_e32 v81, vcc, -1, v13, vcc
	global_load_dword v82, v[80:81], off offset:-3584
	global_load_dword v83, v[80:81], off offset:-3072
	global_load_dword v84, v[80:81], off offset:-2560
	global_load_dword v85, v[80:81], off offset:-2048
	global_load_dword v86, v[80:81], off offset:-1536
	global_load_dword v87, v[80:81], off offset:-1024
	global_load_dword v88, v[80:81], off offset:-512
	global_load_dword v89, v[12:13], off offset:-4096
	global_load_dwordx4 v[74:77], v[78:79], off offset:32
	global_load_dword v90, v[12:13], off offset:-3072
	global_load_dword v91, v[12:13], off offset:-2560
	global_load_dword v92, v[12:13], off offset:-2048
	global_load_dword v93, v[12:13], off offset:-1536
	global_load_dword v94, v[12:13], off offset:-1024
	global_load_dword v95, v[12:13], off offset:-512
	global_load_dword v78, v[12:13], off
	s_addc_u32 s11, s11, 0
	v_lshl_add_u64 v[12:13], v[12:13], 0, s[8:9]
	s_cmpk_eq_i32 s10, 0x400
	s_waitcnt vmcnt(35)
	v_fmac_f32_e32 v9, v30, v42
	s_waitcnt vmcnt(34)
	v_fmac_f32_e32 v9, v31, v43
	s_waitcnt vmcnt(33)
	v_fmac_f32_e32 v9, v32, v44
	s_waitcnt vmcnt(32)
	v_fmac_f32_e32 v9, v33, v45
	s_waitcnt vmcnt(31)
	v_fmac_f32_e32 v9, v26, v46
	s_waitcnt vmcnt(30)
	v_fmac_f32_e32 v9, v27, v47
	s_waitcnt vmcnt(29)
	v_fmac_f32_e32 v9, v28, v48
	s_waitcnt vmcnt(28)
	v_fmac_f32_e32 v9, v29, v49
	s_waitcnt vmcnt(27)
	v_fmac_f32_e32 v9, v34, v6
	s_waitcnt vmcnt(26)
	v_fmac_f32_e32 v9, v35, v50
	s_waitcnt vmcnt(25)
	v_fmac_f32_e32 v9, v36, v51
	s_waitcnt vmcnt(24)
	v_fmac_f32_e32 v9, v37, v52
	s_waitcnt vmcnt(23)
	v_fmac_f32_e32 v9, v22, v53
	s_waitcnt vmcnt(22)
	v_fmac_f32_e32 v9, v23, v54
	s_waitcnt vmcnt(21)
	v_fmac_f32_e32 v9, v24, v55
	s_waitcnt vmcnt(20)
	v_fmac_f32_e32 v9, v25, v38
	s_waitcnt vmcnt(15)
	v_fmac_f32_e32 v9, v70, v82
	s_waitcnt vmcnt(14)
	v_fmac_f32_e32 v9, v71, v83
	s_waitcnt vmcnt(13)
	v_fmac_f32_e32 v9, v72, v84
	s_waitcnt vmcnt(12)
	v_fmac_f32_e32 v9, v73, v85
	s_waitcnt vmcnt(11)
	v_fmac_f32_e32 v9, v66, v86
	s_waitcnt vmcnt(10)
	v_fmac_f32_e32 v9, v67, v87
	s_waitcnt vmcnt(9)
	v_fmac_f32_e32 v9, v68, v88
	s_waitcnt vmcnt(8)
	v_fmac_f32_e32 v9, v69, v89
	s_waitcnt vmcnt(7)
	v_fmac_f32_e32 v9, v74, v96
	s_waitcnt vmcnt(6)
	v_fmac_f32_e32 v9, v75, v90
	s_waitcnt vmcnt(5)
	v_fmac_f32_e32 v9, v76, v91
	s_waitcnt vmcnt(4)
	v_fmac_f32_e32 v9, v77, v92
	s_waitcnt vmcnt(3)
	v_fmac_f32_e32 v9, v62, v93
	s_waitcnt vmcnt(2)
	v_fmac_f32_e32 v9, v63, v94
	s_waitcnt vmcnt(1)
	v_fmac_f32_e32 v9, v64, v95
	s_waitcnt vmcnt(0)
	v_fmac_f32_e32 v9, v65, v78
	s_cbranch_scc0 .LBB0_97
	v_lshlrev_b32_e32 v8, 8, v8
	v_lshlrev_b32_e32 v6, 2, v2
	v_lshl_or_b32 v10, v21, 7, v8
	v_and_or_b32 v6, v6, 64, v14
	v_ashrrev_i32_e32 v11, 31, v10
	v_lshl_add_u64 v[10:11], v[10:11], 2, v[4:5]
	v_lshlrev_b32_e32 v6, 2, v6
	v_lshl_add_u64 v[10:11], v[10:11], 0, v[6:7]
	global_atomic_add_f32 v[10:11], v9, off
	v_add_u32_e32 v2, s16, v2
	v_cmp_lt_i32_e32 vcc, s22, v2
	v_add_u32_e32 v3, s17, v3
	s_or_b64 s[4:5], vcc, s[4:5]
	v_add_u32_e32 v16, s18, v16
	s_andn2_b64 exec, exec, s[4:5]
	s_cbranch_execnz .LBB0_96

; #define LAS __attribute__((address_space(3)))
; DI void nsa_unit(const P& p, ldsp lds, int u, int l, int wv) {
;     ...
;             unsigned th = 0u;
; #pragma unroll 4
;     ...
;                 const unsigned trial = th | (1u << bit);
;                 const int cnt = __popcll(__ballot(k0 >= trial)) + __popcll(__ballot(k1 >= trial));
;                 th = (cnt >= 16) ? trial : th;
;             }
;             const u64 gt0 = __ballot(k0 > th), gt1 = __ballot(k1 > th), eq0 = __ballot(k0 == th), eq1 = __ballot(k1 == th);
;             const int need = 16 - (__popcll(gt0) + __popcll(gt1));
;             const u64 below = (lane == 0) ? 0ull : (~0ull >> (64 - lane));
;             const int pos0 = __popcll(eq0 & below), pos1 = __popcll(eq0) + __popcll(eq1 & below);
;             const bool s0 = (k0 > th) || (k0 == th && pos0 < need), s1 = (k1 > th) || (k1 == th && pos1 < need);
;             const u64 lo = __ballot(s0 && va0), hi = __ballot(s1 && va1);
;             if (lane == 0) { *(LAS u64*)(lds + A_SEL + qq * 16) = lo; *(LAS u64*)(lds + A_SEL + qq * 16 + 8) = hi; }
.LBB0_688:
	s_lshl_b32 s9, 1, s8
	s_or_b32 s9, s9, s12
	v_cmp_le_u32_e64 s[66:67], s9, v71
	v_cmp_le_u32_e32 vcc, s9, v72
	s_bcnt1_i32_b64 s10, s[66:67]
	s_bcnt1_i32_b64 s11, vcc
	s_add_i32 s11, s11, s10
	s_cmp_gt_u32 s11, 15
	s_cselect_b32 s9, s9, s12
	s_add_i32 s10, s8, -1
	s_lshl_b32 s10, 1, s10
	s_or_b32 s10, s10, s9
	v_cmp_le_u32_e64 s[66:67], s10, v71
	v_cmp_le_u32_e32 vcc, s10, v72
	s_bcnt1_i32_b64 s11, s[66:67]
	s_bcnt1_i32_b64 s12, vcc
	s_add_i32 s12, s12, s11
	s_cmp_gt_u32 s12, 15
	s_cselect_b32 s9, s10, s9
	s_add_i32 s10, s8, -2
	s_lshl_b32 s10, 1, s10
	s_or_b32 s10, s10, s9
	v_cmp_le_u32_e64 s[66:67], s10, v71
	v_cmp_le_u32_e32 vcc, s10, v72
	s_bcnt1_i32_b64 s11, s[66:67]
	s_bcnt1_i32_b64 s12, vcc
	s_add_i32 s12, s12, s11
	s_cmp_gt_u32 s12, 15
	s_cselect_b32 s9, s10, s9
	s_add_i32 s8, s8, -3
	s_lshl_b32 s10, 1, s8
	s_or_b32 s10, s10, s9
	v_cmp_le_u32_e64 s[66:67], s10, v71
	v_cmp_le_u32_e32 vcc, s10, v72
	s_bcnt1_i32_b64 s11, s[66:67]
	s_bcnt1_i32_b64 s12, vcc
	s_add_i32 s12, s12, s11
	s_cmp_gt_u32 s12, 15
	s_cselect_b32 s12, s10, s9
	v_sub_co_u32_e64 v0, s[10:11], s8, 1
	s_nop 0
	v_readfirstlane_b32 s8, v0
	s_and_b64 vcc, exec, s[10:11]
	s_cbranch_vccz .LBB0_688
	v_sub_u32_e32 v0, 64, v167
	v_lshrrev_b64 v[74:75], v0, -1
	v_cndmask_b32_e64 v0, v74, 0, s[40:41]
	v_cmp_eq_u32_e64 s[10:11], s12, v71
	v_cndmask_b32_e64 v67, v75, 0, s[40:41]
	v_cmp_lt_u32_e32 vcc, s12, v71
	v_cmp_lt_u32_e64 s[8:9], s12, v72
	v_cmp_eq_u32_e64 s[12:13], s12, v72
	v_and_b32_e32 v72, s10, v0
	s_bcnt1_i32_b64 s14, vcc
	s_bcnt1_i32_b64 s15, s[8:9]
	v_and_b32_e32 v71, s11, v67
	v_bcnt_u32_b32 v72, v72, 0
	v_and_b32_e32 v73, s12, v0
	s_add_i32 s14, s14, s15
	v_bcnt_u32_b32 v71, v71, v72
	v_and_b32_e32 v72, s13, v67
	v_bcnt_u32_b32 v73, v73, 0
	s_sub_i32 s16, 16, s14
	s_bcnt1_i32_b64 s14, s[10:11]
	v_bcnt_u32_b32 v72, v72, v73
	v_add_u32_e32 v72, s14, v72
	v_cmp_gt_i32_e64 s[14:15], s16, v71
	s_and_b64 s[10:11], s[10:11], s[14:15]
	s_or_b64 s[10:11], vcc, s[10:11]
	v_cmp_gt_i32_e32 vcc, s16, v72
	s_and_b64 s[12:13], s[12:13], vcc
	s_or_b64 s[8:9], s[8:9], s[12:13]
	s_and_b64 s[2:3], s[10:11], s[2:3]
	v_cndmask_b32_e64 v71, 0, 1, s[2:3]
	s_and_b64 s[2:3], s[8:9], s[6:7]
	v_cmp_ne_u32_e64 s[56:57], 0, v71
	v_cndmask_b32_e64 v71, 0, 1, s[2:3]
	v_cmp_ne_u32_e64 s[2:3], 0, v71
	s_and_saveexec_b64 s[6:7], s[40:41]
	s_cbranch_execz .LBB0_691
	v_lshl_add_u32 v71, v166, 7, 0
	v_add_u32_e32 v71, 0x21a00, v71
	v_mov_b32_e32 v72, s56
	v_mov_b32_e32 v73, s57
	v_mov_b32_e32 v74, s2
	v_mov_b32_e32 v75, s3
	ds_write_b128 v71, v[72:75]

; #define LAS __attribute__((address_space(3)))
; DI void nsa_unit(const P& p, ldsp lds, int u, int l, int wv) {
;     ...
;             unsigned th = 0u;
; #pragma unroll 4
;     ...
;                 const unsigned trial = th | (1u << bit);
;                 const int cnt = __popcll(__ballot(k0 >= trial)) + __popcll(__ballot(k1 >= trial));
;                 th = (cnt >= 16) ? trial : th;
;             }
;             const u64 gt0 = __ballot(k0 > th), gt1 = __ballot(k1 > th), eq0 = __ballot(k0 == th), eq1 = __ballot(k1 == th);
;             const int need = 16 - (__popcll(gt0) + __popcll(gt1));
;             const u64 below = (lane == 0) ? 0ull : (~0ull >> (64 - lane));
;             const int pos0 = __popcll(eq0 & below), pos1 = __popcll(eq0) + __popcll(eq1 & below);
;             const bool s0 = (k0 > th) || (k0 == th && pos0 < need), s1 = (k1 > th) || (k1 == th && pos1 < need);
;             const u64 lo = __ballot(s0 && va0), hi = __ballot(s1 && va1);
;             if (lane == 0) { *(LAS u64*)(lds + A_SEL + qq * 16) = lo; *(LAS u64*)(lds + A_SEL + qq * 16 + 8) = hi; }
.LBB0_696:
	s_lshl_b32 s11, 1, s10
	s_or_b32 s11, s11, s14
	v_cmp_le_u32_e64 s[66:67], s11, v72
	v_cmp_le_u32_e32 vcc, s11, v73
	s_bcnt1_i32_b64 s12, s[66:67]
	s_bcnt1_i32_b64 s13, vcc
	s_add_i32 s13, s13, s12
	s_cmp_gt_u32 s13, 15
	s_cselect_b32 s11, s11, s14
	s_add_i32 s12, s10, -1
	s_lshl_b32 s12, 1, s12
	s_or_b32 s12, s12, s11
	v_cmp_le_u32_e64 s[66:67], s12, v72
	v_cmp_le_u32_e32 vcc, s12, v73
	s_bcnt1_i32_b64 s13, s[66:67]
	s_bcnt1_i32_b64 s14, vcc
	s_add_i32 s14, s14, s13
	s_cmp_gt_u32 s14, 15
	s_cselect_b32 s11, s12, s11
	s_add_i32 s12, s10, -2
	s_lshl_b32 s12, 1, s12
	s_or_b32 s12, s12, s11
	v_cmp_le_u32_e64 s[66:67], s12, v72
	v_cmp_le_u32_e32 vcc, s12, v73
	s_bcnt1_i32_b64 s13, s[66:67]
	s_bcnt1_i32_b64 s14, vcc
	s_add_i32 s14, s14, s13
	s_cmp_gt_u32 s14, 15
	s_cselect_b32 s11, s12, s11
	s_add_i32 s10, s10, -3
	s_lshl_b32 s12, 1, s10
	s_or_b32 s12, s12, s11
	v_cmp_le_u32_e64 s[66:67], s12, v72
	v_cmp_le_u32_e32 vcc, s12, v73
	s_bcnt1_i32_b64 s13, s[66:67]
	s_bcnt1_i32_b64 s14, vcc
	s_add_i32 s14, s14, s13
	s_cmp_gt_u32 s14, 15
	s_cselect_b32 s14, s12, s11
	v_sub_co_u32_e64 v74, s[12:13], s10, 1
	s_nop 0
	v_readfirstlane_b32 s10, v74
	s_andn2_b64 vcc, exec, s[12:13]
	s_cbranch_vccnz .LBB0_696
	v_cmp_lt_u32_e32 vcc, s14, v72
	v_cmp_lt_u32_e64 s[10:11], s14, v73
	v_cmp_eq_u32_e64 s[12:13], s14, v72
	v_cmp_eq_u32_e64 s[14:15], s14, v73
	s_bcnt1_i32_b64 s16, vcc
	s_bcnt1_i32_b64 s20, s[10:11]
	v_and_b32_e32 v73, s12, v0
	s_add_i32 s16, s16, s20
	v_and_b32_e32 v72, s13, v67
	v_bcnt_u32_b32 v73, v73, 0
	v_and_b32_e32 v74, s14, v0
	s_sub_i32 s16, 16, s16
	v_bcnt_u32_b32 v72, v72, v73
	v_and_b32_e32 v73, s15, v67
	v_bcnt_u32_b32 v74, v74, 0
	s_bcnt1_i32_b64 s20, s[12:13]
	v_bcnt_u32_b32 v73, v73, v74
	v_cmp_gt_i32_e64 s[44:45], s16, v72
	v_add_u32_e32 v73, s20, v73
	s_and_b64 s[12:13], s[12:13], s[44:45]
	s_or_b64 s[12:13], vcc, s[12:13]
	v_cmp_gt_i32_e32 vcc, s16, v73
	s_and_b64 s[14:15], s[14:15], vcc
	s_or_b64 s[10:11], s[10:11], s[14:15]
	s_and_b64 s[6:7], s[12:13], s[6:7]
	v_cndmask_b32_e64 v72, 0, 1, s[6:7]
	s_and_b64 s[6:7], s[10:11], s[8:9]
	v_cmp_ne_u32_e64 s[60:61], 0, v72
	v_cndmask_b32_e64 v72, 0, 1, s[6:7]
	v_cmp_ne_u32_e64 s[6:7], 0, v72
	s_and_saveexec_b64 s[8:9], s[40:41]
	s_cbranch_execz .LBB0_699
	v_lshl_add_u32 v71, v71, 4, 0
	v_add_u32_e32 v71, 0x21a00, v71
	v_mov_b32_e32 v72, s60
	v_mov_b32_e32 v73, s61
	v_mov_b32_e32 v74, s6
	v_mov_b32_e32 v75, s7
	ds_write_b128 v71, v[72:75]

; #define LAS __attribute__((address_space(3)))
; DI void nsa_unit(const P& p, ldsp lds, int u, int l, int wv) {
;     ...
;             unsigned th = 0u;
; #pragma unroll 4
;     ...
;                 const unsigned trial = th | (1u << bit);
;                 const int cnt = __popcll(__ballot(k0 >= trial)) + __popcll(__ballot(k1 >= trial));
;                 th = (cnt >= 16) ? trial : th;
;             }
;             const u64 gt0 = __ballot(k0 > th), gt1 = __ballot(k1 > th), eq0 = __ballot(k0 == th), eq1 = __ballot(k1 == th);
;             const int need = 16 - (__popcll(gt0) + __popcll(gt1));
;             const u64 below = (lane == 0) ? 0ull : (~0ull >> (64 - lane));
;             const int pos0 = __popcll(eq0 & below), pos1 = __popcll(eq0) + __popcll(eq1 & below);
;             const bool s0 = (k0 > th) || (k0 == th && pos0 < need), s1 = (k1 > th) || (k1 == th && pos1 < need);
;             const u64 lo = __ballot(s0 && va0), hi = __ballot(s1 && va1);
;             if (lane == 0) { *(LAS u64*)(lds + A_SEL + qq * 16) = lo; *(LAS u64*)(lds + A_SEL + qq * 16 + 8) = hi; }
.LBB0_704:
	s_lshl_b32 s13, 1, s12
	s_or_b32 s13, s13, s16
	v_cmp_le_u32_e64 s[66:67], s13, v72
	v_cmp_le_u32_e32 vcc, s13, v73
	s_bcnt1_i32_b64 s14, s[66:67]
	s_bcnt1_i32_b64 s15, vcc
	s_add_i32 s15, s15, s14
	s_cmp_gt_u32 s15, 15
	s_cselect_b32 s13, s13, s16
	s_add_i32 s14, s12, -1
	s_lshl_b32 s14, 1, s14
	s_or_b32 s14, s14, s13
	v_cmp_le_u32_e64 s[66:67], s14, v72
	v_cmp_le_u32_e32 vcc, s14, v73
	s_bcnt1_i32_b64 s15, s[66:67]
	s_bcnt1_i32_b64 s16, vcc
	s_add_i32 s16, s16, s15
	s_cmp_gt_u32 s16, 15
	s_cselect_b32 s13, s14, s13
	s_add_i32 s14, s12, -2
	s_lshl_b32 s14, 1, s14
	s_or_b32 s14, s14, s13
	v_cmp_le_u32_e64 s[66:67], s14, v72
	v_cmp_le_u32_e32 vcc, s14, v73
	s_bcnt1_i32_b64 s15, s[66:67]
	s_bcnt1_i32_b64 s16, vcc
	s_add_i32 s16, s16, s15
	s_cmp_gt_u32 s16, 15
	s_cselect_b32 s13, s14, s13
	s_add_i32 s12, s12, -3
	s_lshl_b32 s14, 1, s12
	s_or_b32 s14, s14, s13
	v_cmp_le_u32_e64 s[66:67], s14, v72
	v_cmp_le_u32_e32 vcc, s14, v73
	s_bcnt1_i32_b64 s15, s[66:67]
	s_bcnt1_i32_b64 s16, vcc
	s_add_i32 s16, s16, s15
	s_cmp_gt_u32 s16, 15
	s_cselect_b32 s16, s14, s13
	v_sub_co_u32_e64 v74, s[14:15], s12, 1
	s_nop 0
	v_readfirstlane_b32 s12, v74
	s_andn2_b64 vcc, exec, s[14:15]
	s_cbranch_vccnz .LBB0_704
	v_cmp_lt_u32_e32 vcc, s16, v72
	v_cmp_lt_u32_e64 s[12:13], s16, v73
	v_cmp_eq_u32_e64 s[14:15], s16, v72
	v_cmp_eq_u32_e64 s[44:45], s16, v73
	s_bcnt1_i32_b64 s16, vcc
	s_bcnt1_i32_b64 s20, s[12:13]
	v_and_b32_e32 v73, s14, v0
	s_add_i32 s16, s16, s20
	v_and_b32_e32 v72, s15, v67
	v_bcnt_u32_b32 v73, v73, 0
	v_and_b32_e32 v74, s44, v0
	s_sub_i32 s16, 16, s16
	v_bcnt_u32_b32 v72, v72, v73
	v_and_b32_e32 v73, s45, v67
	v_bcnt_u32_b32 v74, v74, 0
	s_bcnt1_i32_b64 s20, s[14:15]
	v_bcnt_u32_b32 v73, v73, v74
	v_cmp_gt_i32_e64 s[46:47], s16, v72
	v_add_u32_e32 v73, s20, v73
	s_and_b64 s[14:15], s[14:15], s[46:47]
	s_or_b64 s[14:15], vcc, s[14:15]
	v_cmp_gt_i32_e32 vcc, s16, v73
	s_and_b64 s[20:21], s[44:45], vcc
	s_or_b64 s[12:13], s[12:13], s[20:21]
	s_and_b64 s[8:9], s[14:15], s[8:9]
	v_cndmask_b32_e64 v72, 0, 1, s[8:9]
	s_and_b64 s[8:9], s[12:13], s[10:11]
	v_cmp_ne_u32_e64 s[62:63], 0, v72
	v_cndmask_b32_e64 v72, 0, 1, s[8:9]
	v_cmp_ne_u32_e64 s[8:9], 0, v72
	s_and_saveexec_b64 s[10:11], s[40:41]
	s_cbranch_execz .LBB0_707
	v_lshl_add_u32 v71, v71, 4, 0
	v_add_u32_e32 v71, 0x21a00, v71
	v_mov_b32_e32 v72, s62
	v_mov_b32_e32 v73, s63
	v_mov_b32_e32 v74, s8
	v_mov_b32_e32 v75, s9
	ds_write_b128 v71, v[72:75]

; #define LAS __attribute__((address_space(3)))
; DI void nsa_unit(const P& p, ldsp lds, int u, int l, int wv) {
;     ...
;             unsigned th = 0u;
; #pragma unroll 4
;     ...
;                 const unsigned trial = th | (1u << bit);
;                 const int cnt = __popcll(__ballot(k0 >= trial)) + __popcll(__ballot(k1 >= trial));
;                 th = (cnt >= 16) ? trial : th;
;             }
;             const u64 gt0 = __ballot(k0 > th), gt1 = __ballot(k1 > th), eq0 = __ballot(k0 == th), eq1 = __ballot(k1 == th);
;             const int need = 16 - (__popcll(gt0) + __popcll(gt1));
;             const u64 below = (lane == 0) ? 0ull : (~0ull >> (64 - lane));
;             const int pos0 = __popcll(eq0 & below), pos1 = __popcll(eq0) + __popcll(eq1 & below);
;             const bool s0 = (k0 > th) || (k0 == th && pos0 < need), s1 = (k1 > th) || (k1 == th && pos1 < need);
;             const u64 lo = __ballot(s0 && va0), hi = __ballot(s1 && va1);
;             if (lane == 0) { *(LAS u64*)(lds + A_SEL + qq * 16) = lo; *(LAS u64*)(lds + A_SEL + qq * 16 + 8) = hi; }
.LBB0_712:
	s_lshl_b32 s15, 1, s14
	s_or_b32 s15, s15, s16
	v_cmp_le_u32_e64 s[66:67], s15, v72
	v_cmp_le_u32_e32 vcc, s15, v73
	s_bcnt1_i32_b64 s20, s[66:67]
	s_bcnt1_i32_b64 s21, vcc
	s_add_i32 s21, s21, s20
	s_cmp_gt_u32 s21, 15
	s_cselect_b32 s15, s15, s16
	s_add_i32 s16, s14, -1
	s_lshl_b32 s16, 1, s16
	s_or_b32 s16, s16, s15
	v_cmp_le_u32_e64 s[66:67], s16, v72
	v_cmp_le_u32_e32 vcc, s16, v73
	s_bcnt1_i32_b64 s20, s[66:67]
	s_bcnt1_i32_b64 s21, vcc
	s_add_i32 s21, s21, s20
	s_cmp_gt_u32 s21, 15
	s_cselect_b32 s15, s16, s15
	s_add_i32 s16, s14, -2
	s_lshl_b32 s16, 1, s16
	s_or_b32 s16, s16, s15
	v_cmp_le_u32_e64 s[66:67], s16, v72
	v_cmp_le_u32_e32 vcc, s16, v73
	s_bcnt1_i32_b64 s20, s[66:67]
	s_bcnt1_i32_b64 s21, vcc
	s_add_i32 s21, s21, s20
	s_cmp_gt_u32 s21, 15
	s_cselect_b32 s15, s16, s15
	s_add_i32 s14, s14, -3
	s_lshl_b32 s16, 1, s14
	s_or_b32 s16, s16, s15
	v_cmp_le_u32_e64 s[66:67], s16, v72
	v_cmp_le_u32_e32 vcc, s16, v73
	s_bcnt1_i32_b64 s20, s[66:67]
	s_bcnt1_i32_b64 s21, vcc
	s_add_i32 s21, s21, s20
	s_cmp_gt_u32 s21, 15
	v_sub_co_u32_e64 v74, s[20:21], s14, 1
	s_cselect_b32 s16, s16, s15
	v_readfirstlane_b32 s14, v74
	s_andn2_b64 vcc, exec, s[20:21]
	s_cbranch_vccnz .LBB0_712
	v_cmp_lt_u32_e32 vcc, s16, v72
	v_cmp_lt_u32_e64 s[14:15], s16, v73
	v_cmp_eq_u32_e64 s[44:45], s16, v72
	v_cmp_eq_u32_e64 s[46:47], s16, v73
	s_bcnt1_i32_b64 s16, vcc
	s_bcnt1_i32_b64 s20, s[14:15]
	v_and_b32_e32 v73, s44, v0
	s_add_i32 s16, s16, s20
	v_and_b32_e32 v72, s45, v67
	v_bcnt_u32_b32 v73, v73, 0
	v_and_b32_e32 v74, s46, v0
	s_sub_i32 s16, 16, s16
	v_bcnt_u32_b32 v72, v72, v73
	v_and_b32_e32 v73, s47, v67
	v_bcnt_u32_b32 v74, v74, 0
	s_bcnt1_i32_b64 s20, s[44:45]
	v_bcnt_u32_b32 v73, v73, v74
	v_cmp_gt_i32_e64 s[48:49], s16, v72
	v_add_u32_e32 v73, s20, v73
	s_and_b64 s[20:21], s[44:45], s[48:49]
	s_or_b64 s[20:21], vcc, s[20:21]
	v_cmp_gt_i32_e32 vcc, s16, v73
	s_and_b64 s[22:23], s[46:47], vcc
	s_or_b64 s[14:15], s[14:15], s[22:23]
	s_and_b64 s[10:11], s[20:21], s[10:11]
	v_cndmask_b32_e64 v72, 0, 1, s[10:11]
	s_and_b64 s[10:11], s[14:15], s[12:13]
	v_cmp_ne_u32_e64 s[64:65], 0, v72
	v_cndmask_b32_e64 v72, 0, 1, s[10:11]
	v_cmp_ne_u32_e64 s[10:11], 0, v72
	s_and_saveexec_b64 s[12:13], s[40:41]
	s_cbranch_execz .LBB0_715
	v_lshl_add_u32 v71, v71, 4, 0
	v_add_u32_e32 v71, 0x21a00, v71
	v_mov_b32_e32 v72, s64
	v_mov_b32_e32 v73, s65
	v_mov_b32_e32 v74, s10
	v_mov_b32_e32 v75, s11
	ds_write_b128 v71, v[72:75]

; #define LAS __attribute__((address_space(3)))
; DI void nsa_unit(const P& p, ldsp lds, int u, int l, int wv) {
;     ...
;             unsigned th = 0u;
; #pragma unroll 4
;     ...
;                 const unsigned trial = th | (1u << bit);
;                 const int cnt = __popcll(__ballot(k0 >= trial)) + __popcll(__ballot(k1 >= trial));
;                 th = (cnt >= 16) ? trial : th;
;             }
;             const u64 gt0 = __ballot(k0 > th), gt1 = __ballot(k1 > th), eq0 = __ballot(k0 == th), eq1 = __ballot(k1 == th);
;             const int need = 16 - (__popcll(gt0) + __popcll(gt1));
;             const u64 below = (lane == 0) ? 0ull : (~0ull >> (64 - lane));
;             const int pos0 = __popcll(eq0 & below), pos1 = __popcll(eq0) + __popcll(eq1 & below);
;             const bool s0 = (k0 > th) || (k0 == th && pos0 < need), s1 = (k1 > th) || (k1 == th && pos1 < need);
;             const u64 lo = __ballot(s0 && va0), hi = __ballot(s1 && va1);
;             if (lane == 0) { *(LAS u64*)(lds + A_SEL + qq * 16) = lo; *(LAS u64*)(lds + A_SEL + qq * 16 + 8) = hi; }
.LBB0_720:
	s_lshl_b32 s21, 1, s20
	s_or_b32 s21, s21, s16
	v_cmp_le_u32_e64 s[66:67], s21, v72
	v_cmp_le_u32_e32 vcc, s21, v73
	s_bcnt1_i32_b64 s22, s[66:67]
	s_bcnt1_i32_b64 s23, vcc
	s_add_i32 s23, s23, s22
	s_cmp_gt_u32 s23, 15
	s_cselect_b32 s16, s21, s16
	s_add_i32 s21, s20, -1
	s_lshl_b32 s21, 1, s21
	s_or_b32 s21, s21, s16
	v_cmp_le_u32_e64 s[66:67], s21, v72
	v_cmp_le_u32_e32 vcc, s21, v73
	s_bcnt1_i32_b64 s22, s[66:67]
	s_bcnt1_i32_b64 s23, vcc
	s_add_i32 s23, s23, s22
	s_cmp_gt_u32 s23, 15
	s_cselect_b32 s16, s21, s16
	s_add_i32 s21, s20, -2
	s_lshl_b32 s21, 1, s21
	s_or_b32 s21, s21, s16
	v_cmp_le_u32_e64 s[66:67], s21, v72
	v_cmp_le_u32_e32 vcc, s21, v73
	s_bcnt1_i32_b64 s22, s[66:67]
	s_bcnt1_i32_b64 s23, vcc
	s_add_i32 s23, s23, s22
	s_cmp_gt_u32 s23, 15
	s_cselect_b32 s16, s21, s16
	s_add_i32 s20, s20, -3
	s_lshl_b32 s21, 1, s20
	s_or_b32 s21, s21, s16
	v_cmp_le_u32_e64 s[66:67], s21, v72
	v_cmp_le_u32_e32 vcc, s21, v73
	s_bcnt1_i32_b64 s22, s[66:67]
	s_bcnt1_i32_b64 s23, vcc
	s_add_i32 s23, s23, s22
	s_cmp_gt_u32 s23, 15
	v_sub_co_u32_e64 v74, s[22:23], s20, 1
	s_cselect_b32 s16, s21, s16
	v_readfirstlane_b32 s20, v74
	s_andn2_b64 vcc, exec, s[22:23]
	s_cbranch_vccnz .LBB0_720
	v_cmp_lt_u32_e32 vcc, s16, v72
	v_cmp_lt_u32_e64 s[44:45], s16, v73
	v_cmp_eq_u32_e64 s[46:47], s16, v72
	v_cmp_eq_u32_e64 s[48:49], s16, v73
	s_bcnt1_i32_b64 s16, vcc
	s_bcnt1_i32_b64 s20, s[44:45]
	v_and_b32_e32 v73, s46, v0
	s_add_i32 s16, s16, s20
	v_and_b32_e32 v72, s47, v67
	v_bcnt_u32_b32 v73, v73, 0
	v_and_b32_e32 v74, s48, v0
	s_sub_i32 s16, 16, s16
	v_bcnt_u32_b32 v72, v72, v73
	v_and_b32_e32 v73, s49, v67
	v_bcnt_u32_b32 v74, v74, 0
	s_bcnt1_i32_b64 s20, s[46:47]
	v_bcnt_u32_b32 v73, v73, v74
	v_cmp_gt_i32_e64 s[50:51], s16, v72
	v_add_u32_e32 v73, s20, v73
	s_and_b64 s[20:21], s[46:47], s[50:51]
	s_or_b64 s[20:21], vcc, s[20:21]
	v_cmp_gt_i32_e32 vcc, s16, v73
	s_and_b64 s[22:23], s[48:49], vcc
	s_or_b64 s[22:23], s[44:45], s[22:23]
	s_and_b64 s[12:13], s[20:21], s[12:13]
	v_cndmask_b32_e64 v72, 0, 1, s[12:13]
	s_and_b64 s[12:13], s[22:23], s[14:15]
	v_cmp_ne_u32_e64 s[34:35], 0, v72
	v_cndmask_b32_e64 v72, 0, 1, s[12:13]
	v_cmp_ne_u32_e64 s[12:13], 0, v72
	s_and_saveexec_b64 s[14:15], s[40:41]
	s_cbranch_execz .LBB0_723
	v_lshl_add_u32 v71, v71, 4, 0
	v_add_u32_e32 v71, 0x21a00, v71
	v_mov_b32_e32 v72, s34
	v_mov_b32_e32 v73, s35
	v_mov_b32_e32 v74, s12
	v_mov_b32_e32 v75, s13
	ds_write_b128 v71, v[72:75]

; #define LAS __attribute__((address_space(3)))
; DI void nsa_unit(const P& p, ldsp lds, int u, int l, int wv) {
;     ...
;             unsigned th = 0u;
; #pragma unroll 4
;     ...
;                 const unsigned trial = th | (1u << bit);
;                 const int cnt = __popcll(__ballot(k0 >= trial)) + __popcll(__ballot(k1 >= trial));
;                 th = (cnt >= 16) ? trial : th;
;             }
;             const u64 gt0 = __ballot(k0 > th), gt1 = __ballot(k1 > th), eq0 = __ballot(k0 == th), eq1 = __ballot(k1 == th);
;             const int need = 16 - (__popcll(gt0) + __popcll(gt1));
;             const u64 below = (lane == 0) ? 0ull : (~0ull >> (64 - lane));
;             const int pos0 = __popcll(eq0 & below), pos1 = __popcll(eq0) + __popcll(eq1 & below);
;             const bool s0 = (k0 > th) || (k0 == th && pos0 < need), s1 = (k1 > th) || (k1 == th && pos1 < need);
;             const u64 lo = __ballot(s0 && va0), hi = __ballot(s1 && va1);
;             if (lane == 0) { *(LAS u64*)(lds + A_SEL + qq * 16) = lo; *(LAS u64*)(lds + A_SEL + qq * 16 + 8) = hi; }
.LBB0_728:
	s_lshl_b32 s21, 1, s20
	s_or_b32 s21, s21, s16
	v_cmp_le_u32_e64 s[66:67], s21, v72
	v_cmp_le_u32_e32 vcc, s21, v73
	s_bcnt1_i32_b64 s22, s[66:67]
	s_bcnt1_i32_b64 s23, vcc
	s_add_i32 s23, s23, s22
	s_cmp_gt_u32 s23, 15
	s_cselect_b32 s16, s21, s16
	s_add_i32 s21, s20, -1
	s_lshl_b32 s21, 1, s21
	s_or_b32 s21, s21, s16
	v_cmp_le_u32_e64 s[66:67], s21, v72
	v_cmp_le_u32_e32 vcc, s21, v73
	s_bcnt1_i32_b64 s22, s[66:67]
	s_bcnt1_i32_b64 s23, vcc
	s_add_i32 s23, s23, s22
	s_cmp_gt_u32 s23, 15
	s_cselect_b32 s16, s21, s16
	s_add_i32 s21, s20, -2
	s_lshl_b32 s21, 1, s21
	s_or_b32 s21, s21, s16
	v_cmp_le_u32_e64 s[66:67], s21, v72
	v_cmp_le_u32_e32 vcc, s21, v73
	s_bcnt1_i32_b64 s22, s[66:67]
	s_bcnt1_i32_b64 s23, vcc
	s_add_i32 s23, s23, s22
	s_cmp_gt_u32 s23, 15
	s_cselect_b32 s16, s21, s16
	s_add_i32 s20, s20, -3
	s_lshl_b32 s21, 1, s20
	s_or_b32 s21, s21, s16
	v_cmp_le_u32_e64 s[66:67], s21, v72
	v_cmp_le_u32_e32 vcc, s21, v73
	s_bcnt1_i32_b64 s22, s[66:67]
	s_bcnt1_i32_b64 s23, vcc
	s_add_i32 s23, s23, s22
	s_cmp_gt_u32 s23, 15
	v_sub_co_u32_e64 v74, s[22:23], s20, 1
	s_cselect_b32 s16, s21, s16
	v_readfirstlane_b32 s20, v74
	s_andn2_b64 vcc, exec, s[22:23]
	s_cbranch_vccnz .LBB0_728
	v_cmp_lt_u32_e32 vcc, s16, v72
	v_cmp_lt_u32_e64 s[46:47], s16, v73
	v_cmp_eq_u32_e64 s[48:49], s16, v72
	v_cmp_eq_u32_e64 s[50:51], s16, v73
	s_bcnt1_i32_b64 s16, vcc
	s_bcnt1_i32_b64 s20, s[46:47]
	v_and_b32_e32 v73, s48, v0
	s_add_i32 s16, s16, s20
	v_and_b32_e32 v72, s49, v67
	v_bcnt_u32_b32 v73, v73, 0
	v_and_b32_e32 v74, s50, v0
	s_sub_i32 s16, 16, s16
	v_bcnt_u32_b32 v72, v72, v73
	v_and_b32_e32 v73, s51, v67
	v_bcnt_u32_b32 v74, v74, 0
	s_bcnt1_i32_b64 s20, s[48:49]
	v_bcnt_u32_b32 v73, v73, v74
	v_cmp_gt_i32_e64 s[52:53], s16, v72
	v_add_u32_e32 v73, s20, v73
	s_and_b64 s[20:21], s[48:49], s[52:53]
	s_or_b64 s[20:21], vcc, s[20:21]
	v_cmp_gt_i32_e32 vcc, s16, v73
	s_and_b64 s[22:23], s[50:51], vcc
	s_or_b64 s[22:23], s[46:47], s[22:23]
	s_and_b64 s[14:15], s[20:21], s[14:15]
	v_cndmask_b32_e64 v72, 0, 1, s[14:15]
	s_and_b64 s[14:15], s[22:23], s[44:45]
	v_cmp_ne_u32_e64 s[26:27], 0, v72
	v_cndmask_b32_e64 v72, 0, 1, s[14:15]
	v_cmp_ne_u32_e64 s[14:15], 0, v72
	s_and_saveexec_b64 s[30:31], s[40:41]
	s_cbranch_execz .LBB0_731
	v_lshl_add_u32 v71, v71, 4, 0
	v_add_u32_e32 v71, 0x21a00, v71
	v_mov_b32_e32 v72, s26
	v_mov_b32_e32 v73, s27
	v_mov_b32_e32 v74, s14
	v_mov_b32_e32 v75, s15
	ds_write_b128 v71, v[72:75]

; #define LAS __attribute__((address_space(3)))
; DI void nsa_unit(const P& p, ldsp lds, int u, int l, int wv) {
;     ...
;             unsigned th = 0u;
; #pragma unroll 4
;     ...
;                 const unsigned trial = th | (1u << bit);
;                 const int cnt = __popcll(__ballot(k0 >= trial)) + __popcll(__ballot(k1 >= trial));
;                 th = (cnt >= 16) ? trial : th;
;             }
;             const u64 gt0 = __ballot(k0 > th), gt1 = __ballot(k1 > th), eq0 = __ballot(k0 == th), eq1 = __ballot(k1 == th);
;             const int need = 16 - (__popcll(gt0) + __popcll(gt1));
;             const u64 below = (lane == 0) ? 0ull : (~0ull >> (64 - lane));
;             const int pos0 = __popcll(eq0 & below), pos1 = __popcll(eq0) + __popcll(eq1 & below);
;             const bool s0 = (k0 > th) || (k0 == th && pos0 < need), s1 = (k1 > th) || (k1 == th && pos1 < need);
;             const u64 lo = __ballot(s0 && va0), hi = __ballot(s1 && va1);
;             if (lane == 0) { *(LAS u64*)(lds + A_SEL + qq * 16) = lo; *(LAS u64*)(lds + A_SEL + qq * 16 + 8) = hi; }
.LBB0_736:
	s_lshl_b32 s21, 1, s20
	s_or_b32 s21, s21, s16
	v_cmp_le_u32_e64 s[66:67], s21, v72
	v_cmp_le_u32_e32 vcc, s21, v73
	s_bcnt1_i32_b64 s22, s[66:67]
	s_bcnt1_i32_b64 s23, vcc
	s_add_i32 s23, s23, s22
	s_cmp_gt_u32 s23, 15
	s_cselect_b32 s16, s21, s16
	s_add_i32 s21, s20, -1
	s_lshl_b32 s21, 1, s21
	s_or_b32 s21, s21, s16
	v_cmp_le_u32_e64 s[66:67], s21, v72
	v_cmp_le_u32_e32 vcc, s21, v73
	s_bcnt1_i32_b64 s22, s[66:67]
	s_bcnt1_i32_b64 s23, vcc
	s_add_i32 s23, s23, s22
	s_cmp_gt_u32 s23, 15
	s_cselect_b32 s16, s21, s16
	s_add_i32 s21, s20, -2
	s_lshl_b32 s21, 1, s21
	s_or_b32 s21, s21, s16
	v_cmp_le_u32_e64 s[66:67], s21, v72
	v_cmp_le_u32_e32 vcc, s21, v73
	s_bcnt1_i32_b64 s22, s[66:67]
	s_bcnt1_i32_b64 s23, vcc
	s_add_i32 s23, s23, s22
	s_cmp_gt_u32 s23, 15
	s_cselect_b32 s16, s21, s16
	s_add_i32 s20, s20, -3
	s_lshl_b32 s21, 1, s20
	s_or_b32 s21, s21, s16
	v_cmp_le_u32_e64 s[66:67], s21, v72
	v_cmp_le_u32_e32 vcc, s21, v73
	s_bcnt1_i32_b64 s22, s[66:67]
	s_bcnt1_i32_b64 s23, vcc
	s_add_i32 s23, s23, s22
	s_cmp_gt_u32 s23, 15
	v_sub_co_u32_e64 v74, s[22:23], s20, 1
	s_cselect_b32 s16, s21, s16
	v_readfirstlane_b32 s20, v74
	s_andn2_b64 vcc, exec, s[22:23]
	s_cbranch_vccnz .LBB0_736
	v_cmp_lt_u32_e32 vcc, s16, v72
	v_cmp_lt_u32_e64 s[48:49], s16, v73
	v_cmp_eq_u32_e64 s[50:51], s16, v72
	v_cmp_eq_u32_e64 s[52:53], s16, v73
	s_bcnt1_i32_b64 s16, vcc
	s_bcnt1_i32_b64 s20, s[48:49]
	v_and_b32_e32 v73, s50, v0
	s_add_i32 s16, s16, s20
	v_and_b32_e32 v72, s51, v67
	v_bcnt_u32_b32 v73, v73, 0
	v_and_b32_e32 v74, s52, v0
	s_sub_i32 s16, 16, s16
	v_bcnt_u32_b32 v72, v72, v73
	v_and_b32_e32 v73, s53, v67
	v_bcnt_u32_b32 v74, v74, 0
	s_bcnt1_i32_b64 s20, s[50:51]
	v_bcnt_u32_b32 v73, v73, v74
	v_cmp_gt_i32_e64 s[54:55], s16, v72
	v_add_u32_e32 v73, s20, v73
	s_and_b64 s[20:21], s[50:51], s[54:55]
	s_or_b64 s[20:21], vcc, s[20:21]
	v_cmp_gt_i32_e32 vcc, s16, v73
	s_and_b64 s[22:23], s[52:53], vcc
	s_or_b64 s[22:23], s[48:49], s[22:23]
	s_and_b64 s[20:21], s[20:21], s[44:45]
	v_cndmask_b32_e64 v72, 0, 1, s[20:21]
	s_and_b64 s[20:21], s[22:23], s[46:47]
	v_cmp_ne_u32_e64 s[30:31], 0, v72
	v_cndmask_b32_e64 v72, 0, 1, s[20:21]
	v_cmp_ne_u32_e64 s[44:45], 0, v72
	s_and_saveexec_b64 s[46:47], s[40:41]
	s_cbranch_execz .LBB0_739
	v_lshl_add_u32 v71, v71, 4, 0
	v_add_u32_e32 v71, 0x21a00, v71
	v_mov_b32_e32 v72, s30
	v_mov_b32_e32 v73, s31
	v_mov_b32_e32 v74, s44
	v_mov_b32_e32 v75, s45
	ds_write_b128 v71, v[72:75]

; #define LAS __attribute__((address_space(3)))
; DI void nsa_unit(const P& p, ldsp lds, int u, int l, int wv) {
;     ...
;             unsigned th = 0u;
; #pragma unroll 4
;     ...
;                 const unsigned trial = th | (1u << bit);
;                 const int cnt = __popcll(__ballot(k0 >= trial)) + __popcll(__ballot(k1 >= trial));
;                 th = (cnt >= 16) ? trial : th;
;             }
;             const u64 gt0 = __ballot(k0 > th), gt1 = __ballot(k1 > th), eq0 = __ballot(k0 == th), eq1 = __ballot(k1 == th);
;             const int need = 16 - (__popcll(gt0) + __popcll(gt1));
;             const u64 below = (lane == 0) ? 0ull : (~0ull >> (64 - lane));
;             const int pos0 = __popcll(eq0 & below), pos1 = __popcll(eq0) + __popcll(eq1 & below);
;             const bool s0 = (k0 > th) || (k0 == th && pos0 < need), s1 = (k1 > th) || (k1 == th && pos1 < need);
;             const u64 lo = __ballot(s0 && va0), hi = __ballot(s1 && va1);
;             if (lane == 0) { *(LAS u64*)(lds + A_SEL + qq * 16) = lo; *(LAS u64*)(lds + A_SEL + qq * 16 + 8) = hi; }
.LBB0_744:
	s_lshl_b32 s5, 1, s4
	s_or_b32 s5, s5, s1
	v_cmp_le_u32_e64 s[66:67], s5, v66
	v_cmp_le_u32_e32 vcc, s5, v68
	s_bcnt1_i32_b64 s16, s[66:67]
	s_bcnt1_i32_b64 s20, vcc
	s_add_i32 s20, s20, s16
	s_cmp_gt_u32 s20, 15
	s_cselect_b32 s1, s5, s1
	s_add_i32 s5, s4, -1
	s_lshl_b32 s5, 1, s5
	s_or_b32 s5, s5, s1
	v_cmp_le_u32_e64 s[66:67], s5, v66
	v_cmp_le_u32_e32 vcc, s5, v68
	s_bcnt1_i32_b64 s16, s[66:67]
	s_bcnt1_i32_b64 s20, vcc
	s_add_i32 s20, s20, s16
	s_cmp_gt_u32 s20, 15
	s_cselect_b32 s1, s5, s1
	s_add_i32 s5, s4, -2
	s_lshl_b32 s5, 1, s5
	s_or_b32 s5, s5, s1
	v_cmp_le_u32_e64 s[66:67], s5, v66
	v_cmp_le_u32_e32 vcc, s5, v68
	s_bcnt1_i32_b64 s16, s[66:67]
	s_bcnt1_i32_b64 s20, vcc
	s_add_i32 s20, s20, s16
	s_cmp_gt_u32 s20, 15
	s_cselect_b32 s1, s5, s1
	s_add_i32 s4, s4, -3
	s_lshl_b32 s5, 1, s4
	s_or_b32 s5, s5, s1
	v_cmp_le_u32_e64 s[66:67], s5, v66
	v_cmp_le_u32_e32 vcc, s5, v68
	s_bcnt1_i32_b64 s16, s[66:67]
	s_bcnt1_i32_b64 s20, vcc
	s_add_i32 s20, s20, s16
	s_cmp_gt_u32 s20, 15
	v_sub_co_u32_e64 v69, s[20:21], s4, 1
	s_cselect_b32 s1, s5, s1
	v_readfirstlane_b32 s4, v69
	s_andn2_b64 vcc, exec, s[20:21]
	s_cbranch_vccnz .LBB0_744
	v_cmp_lt_u32_e32 vcc, s1, v66
	v_cmp_lt_u32_e64 s[4:5], s1, v68
	v_cmp_eq_u32_e64 s[50:51], s1, v66
	v_cmp_eq_u32_e64 s[52:53], s1, v68
	s_bcnt1_i32_b64 s1, vcc
	s_bcnt1_i32_b64 s16, s[4:5]
	v_and_b32_e32 v68, s50, v0
	s_add_i32 s1, s1, s16
	v_and_b32_e32 v66, s51, v67
	v_bcnt_u32_b32 v68, v68, 0
	v_and_b32_e32 v0, s52, v0
	s_sub_i32 s1, 16, s1
	v_bcnt_u32_b32 v66, v66, v68
	v_and_b32_e32 v67, s53, v67
	v_bcnt_u32_b32 v0, v0, 0
	s_bcnt1_i32_b64 s16, s[50:51]
	v_bcnt_u32_b32 v0, v67, v0
	v_cmp_gt_i32_e64 s[54:55], s1, v66
	v_add_u32_e32 v0, s16, v0
	s_and_b64 s[20:21], s[50:51], s[54:55]
	s_or_b64 s[20:21], vcc, s[20:21]
	v_cmp_gt_i32_e32 vcc, s1, v0
	s_and_b64 s[22:23], s[52:53], vcc
	s_or_b64 s[22:23], s[4:5], s[22:23]
	s_and_b64 s[4:5], s[20:21], s[46:47]
	v_cndmask_b32_e64 v0, 0, 1, s[4:5]
	s_and_b64 s[20:21], s[22:23], s[48:49]
	v_cmp_ne_u32_e64 s[4:5], 0, v0
	v_cndmask_b32_e64 v0, 0, 1, s[20:21]
	v_cmp_ne_u32_e32 vcc, 0, v0
	s_and_saveexec_b64 s[46:47], s[40:41]
	s_cbranch_execz .LBB0_747
	v_lshl_add_u32 v0, v71, 4, 0
	v_add_u32_e32 v0, 0x21a00, v0
	v_mov_b32_e32 v66, s4
	v_mov_b32_e32 v67, s5
	v_mov_b32_e32 v68, vcc_lo
	v_mov_b32_e32 v69, vcc_hi
	ds_write_b128 v0, v[66:69]

; template <int MODE> DI void attn_run(AttnCtx& c, const bf16x8 (&q)[8], f32x16 (&o)[4], ldsp lds, int tid, int wv) {
;     ...
;         const int cur = i & 1, tj = TILE_ID(i);
;         const int m3n = STAG ? (m3 == 2 ? 0 : m3 + 1) : (m3 ^ 1);
;         float cb_next = 0.f;
;         if (MODE == MD_FOX || ((MODE == MD_SEL || MODE == MD_CMP1 || MODE == MD_CMP2) && c.xsel)) {
;             if (i > 0) {
;                 unsigned any = 0u;
; #pragma unroll
;                 for (int k = 0; k < NWAVES; ++k) any |= xflag[((i - 1) & 1) * NWAVES + k];
;                 if (any == 0u) break;
;             }
;             if (MODE == MD_FOX) { if (i + 1 < c.ntiles) cb_next = c.cumb[(size_t)TILE_ID(i + 1) * 64 + 63]; }
;             else if (MODE == MD_SEL) { if (i + 1 < c.ntiles) cb_next = -c.slope2 * (float)(c.t - (TILE_ID(i + 1) * 64 + 63)); }
.LBB0_899:
	s_add_i32 s2, s34, -4
	v_mov_b32_e32 v0, s2
	ds_read2_b32 v[144:145], v0 offset1:1
	s_and_b64 vcc, exec, s[54:55]
	s_waitcnt lgkmcnt(0)
	v_readfirstlane_b32 s22, v144
	s_cbranch_vccz .LBB0_925
	s_and_b32 s2, s31, 8
	s_xor_b32 s3, s2, 8
	s_add_i32 s4, 0, 0x22180
	s_lshl_b32 s3, s3, 2
	s_add_i32 s3, s4, s3
	v_mov_b32_e32 v0, s3
	ds_read_b128 v[130:133], v0
	ds_read_b128 v[134:137], v0 offset:16
	s_mov_b64 s[4:5], 0
	s_mov_b64 s[2:3], 0
	s_waitcnt lgkmcnt(0)
	v_or3_b32 v0, v130, v131, v132
	v_or3_b32 v2, v133, v134, v135
	v_or3_b32 v0, v0, v136, v137
	v_or_b32_e32 v0, v0, v2
	v_cmp_ne_u32_e32 vcc, 0, v0
	s_cbranch_vccz .LBB0_904
	s_cmp_ge_i32 s21, s30
	v_mov_b32_e32 v190, 0
	s_cbranch_scc1 .LBB0_903
	v_mov_b32_e32 v0, v145
	v_lshlrev_b32_e32 v0, 6, v0
	v_sub_u32_e32 v0, v211, v0
	v_cvt_f32_i32_e32 v0, v0
	v_mul_f32_e64 v190, -v146, v0

; template <int MODE> DI void tile_gload(TileRegs& r, const bf16* kt, const bf16* vt, size_t vpitch, const float* bias, int tid) {
;     r.k0 = *(const u32x4*)(kt + tid * 8); r.k1 = *(const u32x4*)(kt + (tid + 512) * 8);
;     if (MODE != MD_CMP1) {
;         r.v0 = *(const u32x4*)(vt + tid * 8);
;         r.v1 = *(const u32x4*)(vt + (tid + 512) * 8);
;     }
; template <int MODE> DI void attn_run(AttnCtx& c, const bf16x8 (&q)[8], f32x16 (&o)[4], ldsp lds, int tid, int wv) {
;     ...
;         if (i + 1 < c.ntiles) { const int tn = TILE_ID(i + 1);
;             tile_gload<MODE>(tr, c.kmat + (size_t)tn * 64 * HD, c.vtm + (size_t)tn * 8192, c.vpitch, c.cumb + (size_t)tn * 64, tid); }
.LBB0_906:
	s_andn2_b64 vcc, exec, s[4:5]
	s_mov_b64 s[24:25], -1
	s_cbranch_vccnz .LBB0_926
	s_cmp_lt_i32 s21, s30
	s_cselect_b64 s[44:45], -1, 0
	s_cmp_ge_i32 s21, s30
	s_cselect_b64 s[24:25], -1, 0
	s_and_b64 vcc, exec, s[24:25]
	s_cbranch_vccnz .LBB0_909
	v_mov_b32_e32 v2, v145
	v_ashrrev_i32_e32 v3, 31, v2
	v_lshlrev_b64 v[2:3], 14, v[2:3]
	v_lshl_add_u64 v[4:5], s[12:13], 0, v[2:3]
	v_lshl_add_u64 v[2:3], s[14:15], 0, v[2:3]
	v_lshl_add_u64 v[6:7], v[4:5], 0, v[150:151]
	v_lshl_add_u64 v[8:9], v[2:3], 0, v[150:151]
	v_lshl_add_u64 v[4:5], v[4:5], 0, v[152:153]
	global_load_dwordx4 v[130:133], v[6:7], off
	global_load_dwordx4 v[134:137], v[4:5], off
	v_lshl_add_u64 v[2:3], v[2:3], 0, v[152:153]
	global_load_dwordx4 v[138:141], v[8:9], off
	global_load_dwordx4 v[142:145], v[2:3], off
